# Up sample-row small GEMM K-loop software-pipelined two K-steps deep, on top of the P7 one
# baseline (speedup 1.0000x reference)
;     ...
;         for (int i = 0; i < 16; ++i) { acc0[i] = 0.f; acc1[i] = 0.f; }
;         float q8[8];
; #pragma unroll
;         for (int i = 0; i < 8; ++i) q8[i] = 0.f;
;         int rb = 0, cg = 0;
;         if (act) {
;             rb = task / ncg; cg = task - rb * ncg;
;             const int Kw = K / KS, nb = Kw / 64, k0 = ks * Kw;
;             const bf16_t* b0p = Bt + (size_t)(E.brow(cg, 0) + (lane >> 3)) * K + k0 + 8 * (lane & 7);
;             const bf16_t* b1p = Bt + (size_t)(E.brow(cg, 1) + (lane >> 3)) * K + k0 + 8 * (lane & 7);
;             const float* afp = (const float*)Abase + (size_t)(32 * rb + (lane >> 4)) * K + k0 + 4 * (lane & 15);
;             const bf16_t* abp = (const bf16_t*)Abase + (size_t)(32 * rb + (lane >> 3)) * K + k0 + 8 * (lane & 7);
;             f32x4 xa[8]; u32x4 ab[4], bb0[4], bb1[4];
;     ...
;             SG_LOAD(0);
.LBB0_1244:
	s_mul_i32 s18, s25, s80
	s_add_i32 s18, s18, s72
	s_lshl_b32 s18, s18, 2
	s_add_i32 s18, s18, s24
	s_cmpk_lt_i32 s18, 0x400
	s_cselect_b64 s[20:21], -1, 0
	s_cmpk_gt_i32 s18, 0x3ff
	s_cbranch_scc1 .LBB0_1248
	s_ashr_i32 s19, s18, 31
	s_lshr_b32 s19, s19, 26
	s_add_i32 s19, s18, s19
	s_ashr_i32 s19, s19, 6
	s_lshl_b32 s27, s19, 5
	v_or_b32_e32 v6, s27, v123
	v_ashrrev_i32_e32 v7, 31, v6
	v_lshlrev_b64 v[6:7], 12, v[6:7]
	v_lshl_add_u64 v[8:9], v[100:101], 0, v[6:7]
	v_add_co_u32_e32 v10, vcc, s84, v8
	s_lshl_b32 s22, s19, 12
	s_nop 0
	v_addc_co_u32_e32 v11, vcc, 0, v9, vcc
	global_load_dwordx4 v[38:41], v[8:9], off
	s_waitcnt lgkmcnt(0)
	global_load_dwordx4 v[34:37], v[10:11], off
	v_add_co_u32_e32 v10, vcc, s39, v8
	s_mov_b32 s19, 0x14000
	s_nop 0
	v_addc_co_u32_e32 v11, vcc, 0, v9, vcc
	v_add_co_u32_e32 v12, vcc, s38, v8
	s_lshl_b32 s18, s18, 6
	s_nop 0
	v_addc_co_u32_e32 v13, vcc, 0, v9, vcc
	global_load_dwordx4 v[46:49], v[10:11], off
	global_load_dwordx4 v[42:45], v[12:13], off
	v_add_co_u32_e32 v10, vcc, s70, v8
	s_sub_i32 s18, s18, s22
	s_nop 0
	v_addc_co_u32_e32 v11, vcc, 0, v9, vcc
	v_add_co_u32_e32 v12, vcc, s19, v8
	s_mov_b32 s19, 0x18000
	s_nop 0
	v_addc_co_u32_e32 v13, vcc, 0, v9, vcc
	v_or_b32_e32 v2, s18, v122
	global_load_dwordx4 v[54:57], v[10:11], off
	global_load_dwordx4 v[50:53], v[12:13], off
	v_add_co_u32_e32 v10, vcc, s19, v8
	v_ashrrev_i32_e32 v3, 31, v2
	s_nop 0
	v_addc_co_u32_e32 v11, vcc, 0, v9, vcc
	v_lshlrev_b64 v[4:5], 11, v[2:3]
	v_or_b32_e32 v2, 32, v2
	v_add_co_u32_e32 v8, vcc, s71, v8
	v_ashrrev_i32_e32 v3, 31, v2
	s_nop 0
	v_addc_co_u32_e32 v9, vcc, 0, v9, vcc
	v_lshl_add_u64 v[4:5], v[98:99], 0, v[4:5]
	v_lshlrev_b64 v[2:3], 11, v[2:3]
	global_load_dwordx4 v[62:65], v[10:11], off
	global_load_dwordx4 v[58:61], v[8:9], off
	v_add_co_u32_e32 v8, vcc, s84, v4
	v_lshl_add_u64 v[2:3], v[98:99], 0, v[2:3]
	s_nop 0
	v_addc_co_u32_e32 v9, vcc, 0, v5, vcc
	v_add_co_u32_e32 v10, vcc, s84, v2
	global_load_dwordx4 v[66:69], v[4:5], off
	global_load_dwordx4 v[70:73], v[2:3], off
	v_addc_co_u32_e32 v11, vcc, 0, v3, vcc
	global_load_dwordx4 v[74:77], v[8:9], off
	global_load_dwordx4 v[78:81], v[10:11], off
	v_add_co_u32_e32 v8, vcc, s39, v4
	v_lshl_add_u64 v[114:115], v[104:105], 0, v[6:7]
	s_nop 0
	v_addc_co_u32_e32 v9, vcc, 0, v5, vcc
	v_add_co_u32_e32 v10, vcc, s39, v2
	s_nop 1
	v_addc_co_u32_e32 v11, vcc, 0, v3, vcc
	v_add_co_u32_e32 v4, vcc, s38, v4
	global_load_dwordx4 v[82:85], v[8:9], off
	global_load_dwordx4 v[86:89], v[10:11], off
	v_addc_co_u32_e32 v5, vcc, 0, v5, vcc
	v_add_co_u32_e32 v2, vcc, s38, v2
	s_nop 1
	v_addc_co_u32_e32 v3, vcc, 0, v3, vcc
	global_load_dwordx4 v[90:93], v[4:5], off
	global_load_dwordx4 v[94:97], v[2:3], off
	v_subrev_u32_e32 v2, s22, v0
	v_ashrrev_i32_e32 v3, 31, v2
	v_lshlrev_b64 v[2:3], 11, v[2:3]
	v_lshl_add_u64 v[118:119], v[106:107], 0, v[2:3]
	v_subrev_u32_e32 v2, s22, v128
	v_ashrrev_i32_e32 v3, 31, v2
	v_lshlrev_b64 v[2:3], 11, v[2:3]
	v_lshl_add_u64 v[120:121], v[106:107], 0, v[2:3]
	v_mov_b32_e32 v2, 0
	s_mov_b64 s[22:23], 0
	v_mov_b32_e32 v3, v2
	v_mov_b32_e32 v4, v2
	v_mov_b32_e32 v5, v2
	v_mov_b32_e32 v6, v2
	v_mov_b32_e32 v7, v2
	v_mov_b32_e32 v8, v2
	v_mov_b32_e32 v9, v2
	v_mov_b32_e32 v10, v2
	v_mov_b32_e32 v11, v2
	v_mov_b32_e32 v12, v2
	v_mov_b32_e32 v13, v2
	v_mov_b32_e32 v14, v2
	v_mov_b32_e32 v15, v2
	v_mov_b32_e32 v16, v2
	v_mov_b32_e32 v17, v2
	v_mov_b32_e32 v18, v2
	v_mov_b32_e32 v19, v2
	v_mov_b32_e32 v20, v2
	v_mov_b32_e32 v21, v2
	v_mov_b32_e32 v22, v2
	v_mov_b32_e32 v23, v2
	v_mov_b32_e32 v24, v2
	v_mov_b32_e32 v25, v2
	v_mov_b32_e32 v26, v2
	v_mov_b32_e32 v27, v2
	v_mov_b32_e32 v28, v2
	v_mov_b32_e32 v29, v2
	v_mov_b32_e32 v30, v2
	v_mov_b32_e32 v31, v2
	v_mov_b32_e32 v32, v2
	v_mov_b32_e32 v33, v2
	v_mov_b32_e32 v116, v2
	v_mov_b32_e32 v117, v2
	v_mov_b32_e32 v112, v2
	v_mov_b32_e32 v113, v2
	v_mov_b32_e32 v110, v2
	v_mov_b32_e32 v111, v2
	v_mov_b32_e32 v108, v2
	v_mov_b32_e32 v109, v2
	v_lshl_add_u64 v[182:183], v[114:115], 0, s[22:23]
	s_brev_b32 s19, 32
	v_add_co_u32_e32 v144, vcc, s19, v182
	s_mov_b32 s19, 0x4004000
	s_nop 0
	v_addc_co_u32_e32 v145, vcc, 0, v183, vcc
	v_add_co_u32_e32 v146, vcc, s19, v182
	s_mov_b32 s19, 0x4008000
	s_nop 0
	v_addc_co_u32_e32 v147, vcc, 0, v183, vcc
	v_add_co_u32_e32 v152, vcc, s19, v182
	s_mov_b32 s19, 0x400c000
	s_nop 0
	v_addc_co_u32_e32 v153, vcc, 0, v183, vcc
	v_add_co_u32_e32 v154, vcc, s19, v182
	s_mov_b32 s19, 0x4010000
	s_nop 0
	v_addc_co_u32_e32 v155, vcc, 0, v183, vcc
	v_add_co_u32_e32 v174, vcc, s19, v182
	s_mov_b32 s19, 0x4014000
	s_nop 0
	v_addc_co_u32_e32 v175, vcc, 0, v183, vcc
	v_add_co_u32_e32 v176, vcc, s19, v182
	s_mov_b32 s19, 0x4018000
	s_nop 0
	v_addc_co_u32_e32 v177, vcc, 0, v183, vcc
	v_add_co_u32_e32 v184, vcc, s19, v182
	s_mov_b32 s19, 0x401c000
	s_nop 0
	v_addc_co_u32_e32 v185, vcc, 0, v183, vcc
	v_add_co_u32_e32 v182, vcc, s19, v182
	v_lshl_add_u64 v[224:225], v[118:119], 0, s[4:5]
	s_nop 0
	v_addc_co_u32_e32 v183, vcc, 0, v183, vcc
	v_add_co_u32_e32 v190, vcc, s34, v224
	v_lshl_add_u64 v[228:229], v[120:121], 0, s[4:5]
	s_nop 0
	v_addc_co_u32_e32 v191, vcc, 0, v225, vcc
	v_add_co_u32_e32 v194, vcc, s34, v228
	global_load_dwordx4 v[148:151], v[144:145], off offset:256
	s_nop 0
	global_load_dwordx4 v[144:147], v[146:147], off offset:256
	v_addc_co_u32_e32 v195, vcc, 0, v229, vcc
	v_add_co_u32_e32 v208, vcc, s33, v224
	global_load_dwordx4 v[156:159], v[152:153], off offset:256
	s_nop 0
	global_load_dwordx4 v[152:155], v[154:155], off offset:256
	v_addc_co_u32_e32 v209, vcc, 0, v225, vcc
	v_add_co_u32_e32 v212, vcc, s33, v228
	global_load_dwordx4 v[178:181], v[174:175], off offset:256
	s_nop 0
	global_load_dwordx4 v[174:177], v[176:177], off offset:256
	v_addc_co_u32_e32 v213, vcc, 0, v229, vcc
	v_add_co_u32_e32 v216, vcc, s35, v224
	global_load_dwordx4 v[186:189], v[184:185], off offset:256
	s_nop 0
	global_load_dwordx4 v[182:185], v[182:183], off offset:256
	v_addc_co_u32_e32 v217, vcc, 0, v225, vcc
	v_add_co_u32_e32 v220, vcc, s35, v228
	global_load_dwordx4 v[190:193], v[190:191], off offset:128
	s_nop 0
	v_addc_co_u32_e32 v221, vcc, 0, v229, vcc
	v_add_co_u32_e32 v224, vcc, s86, v224
	global_load_dwordx4 v[194:197], v[194:195], off offset:128
	s_nop 0
	v_addc_co_u32_e32 v225, vcc, 0, v225, vcc
	v_add_co_u32_e32 v228, vcc, s86, v228
	global_load_dwordx4 v[208:211], v[208:209], off offset:128
	s_nop 0
	v_addc_co_u32_e32 v229, vcc, 0, v229, vcc
	global_load_dwordx4 v[212:215], v[212:213], off offset:128
	s_nop 0
	global_load_dwordx4 v[216:219], v[216:217], off offset:128
	s_nop 0
	global_load_dwordx4 v[220:223], v[220:221], off offset:128
	s_nop 0
	global_load_dwordx4 v[224:227], v[224:225], off offset:128
	s_nop 0
	global_load_dwordx4 v[228:231], v[228:229], off offset:128
; #define LAS __attribute__((address_space(3)))
; __device__ __forceinline__ unsigned cvtpk(float lo, float hi) { f32x2 v = {lo, hi}; bf16x2_t b = __builtin_convertvector(v, bf16x2_t); return __builtin_bit_cast(unsigned, b); }
;     ...
;             for (int kb = 0; kb < nb; ++kb) {
;                 __builtin_amdgcn_sched_barrier(0);
;                 if constexpr (AF32) {
; #pragma unroll
;                     for (int i = 0; i < 8; ++i) { const f32x4 x = xa[i]; q8[i] += (x[0] * x[0] + x[1] * x[1]) + (x[2] * x[2] + x[3] * x[3]);
;                         u32x2 w; w.x = cvtpk(x[0], x[1]); w.y = cvtpk(x[2], x[3]); *(LAS u32x2*)(SA + (4 * i + (lane >> 4)) * PITCH + 8 * (lane & 15)) = w; }
;                 } else {
; #pragma unroll
;                     for (int i = 0; i < 4; ++i) *(LAS u32x4*)(SA + (8 * i + (lane >> 3)) * PITCH + 16 * (lane & 7)) = ab[i];
;                 }
; #pragma unroll
;                 for (int i = 0; i < 4; ++i) { *(LAS u32x4*)(SB0 + (8 * i + (lane >> 3)) * PITCH + 16 * (lane & 7)) = bb0[i]; *(LAS u32x4*)(SB1 + (8 * i + (lane >> 3)) * PITCH + 16 * (lane & 7)) = bb1[i]; }
;                 __builtin_amdgcn_sched_barrier(0);
;                 if (kb + 1 < nb) SG_LOAD(kb + 1);
.LBB0_1246:
	s_waitcnt vmcnt(31)
	v_cvt_pk_bf16_f32 v134, v38, v39
	v_mov_b32_e32 v136, v38
	v_mov_b32_e32 v38, v39
	s_waitcnt vmcnt(30)
	v_mov_b32_e32 v39, v35
	v_mov_b32_e32 v137, v34
	v_pk_mul_f32 v[38:39], v[38:39], v[38:39]
	v_cvt_pk_bf16_f32 v135, v40, v41
	v_pk_fma_f32 v[38:39], v[136:137], v[136:137], v[38:39]
	v_mov_b32_e32 v136, v40
	v_mov_b32_e32 v40, v41
	v_mov_b32_e32 v41, v37
	v_mov_b32_e32 v137, v36
	v_pk_mul_f32 v[40:41], v[40:41], v[40:41]
	v_cvt_pk_bf16_f32 v34, v34, v35
	v_pk_fma_f32 v[40:41], v[136:137], v[136:137], v[40:41]
	v_cvt_pk_bf16_f32 v35, v36, v37
	v_pk_add_f32 v[38:39], v[38:39], v[40:41]
	s_waitcnt vmcnt(29)
	v_mov_b32_e32 v36, v46
	v_pk_add_f32 v[108:109], v[108:109], v[38:39]
	v_mov_b32_e32 v38, v47
	s_waitcnt vmcnt(28)
	v_mov_b32_e32 v39, v43
	v_mov_b32_e32 v37, v42
	v_pk_mul_f32 v[38:39], v[38:39], v[38:39]
	v_mov_b32_e32 v40, v49
	v_mov_b32_e32 v41, v45
	v_pk_fma_f32 v[36:37], v[36:37], v[36:37], v[38:39]
	v_mov_b32_e32 v38, v48
	v_mov_b32_e32 v39, v44
	v_pk_mul_f32 v[40:41], v[40:41], v[40:41]
	ds_write2_b64 v130, v[134:135], v[34:35] offset1:72
	v_pk_fma_f32 v[38:39], v[38:39], v[38:39], v[40:41]
	v_cvt_pk_bf16_f32 v34, v46, v47
	v_pk_add_f32 v[36:37], v[36:37], v[38:39]
	v_cvt_pk_bf16_f32 v35, v48, v49
	v_pk_add_f32 v[110:111], v[110:111], v[36:37]
	v_cvt_pk_bf16_f32 v36, v42, v43
	v_cvt_pk_bf16_f32 v37, v44, v45
	s_waitcnt vmcnt(27)
	v_mov_b32_e32 v38, v55
	s_waitcnt vmcnt(26)
	v_mov_b32_e32 v39, v51
	ds_write2_b64 v130, v[34:35], v[36:37] offset0:144 offset1:216
	v_mov_b32_e32 v36, v54
	v_mov_b32_e32 v37, v50
	v_pk_mul_f32 v[38:39], v[38:39], v[38:39]
	v_mov_b32_e32 v40, v57
	v_mov_b32_e32 v41, v53
	v_pk_fma_f32 v[36:37], v[36:37], v[36:37], v[38:39]
	v_mov_b32_e32 v38, v56
	v_mov_b32_e32 v39, v52
	v_pk_mul_f32 v[40:41], v[40:41], v[40:41]
	v_cvt_pk_bf16_f32 v34, v54, v55
	v_pk_fma_f32 v[38:39], v[38:39], v[38:39], v[40:41]
	v_cvt_pk_bf16_f32 v35, v56, v57
	v_pk_add_f32 v[36:37], v[36:37], v[38:39]
	v_add_u32_e32 v134, 0x800, v130
	v_pk_add_f32 v[112:113], v[112:113], v[36:37]
	v_cvt_pk_bf16_f32 v36, v50, v51
	v_cvt_pk_bf16_f32 v37, v52, v53
	s_waitcnt vmcnt(25)
	v_mov_b32_e32 v38, v63
	s_waitcnt vmcnt(24)
	v_mov_b32_e32 v39, v59
	ds_write2_b64 v134, v[34:35], v[36:37] offset0:32 offset1:104
	v_mov_b32_e32 v36, v62
	v_mov_b32_e32 v37, v58
	v_pk_mul_f32 v[38:39], v[38:39], v[38:39]
	v_mov_b32_e32 v40, v65
	v_mov_b32_e32 v41, v61
	v_pk_fma_f32 v[36:37], v[36:37], v[36:37], v[38:39]
	v_mov_b32_e32 v38, v64
	v_mov_b32_e32 v39, v60
	v_pk_mul_f32 v[40:41], v[40:41], v[40:41]
	v_cvt_pk_bf16_f32 v34, v62, v63
	v_pk_fma_f32 v[38:39], v[38:39], v[38:39], v[40:41]
	v_cvt_pk_bf16_f32 v35, v64, v65
	v_pk_add_f32 v[36:37], v[36:37], v[38:39]
	s_nop 0
	v_pk_add_f32 v[116:117], v[116:117], v[36:37]
	v_cvt_pk_bf16_f32 v36, v58, v59
	v_cvt_pk_bf16_f32 v37, v60, v61
	ds_write2_b64 v134, v[34:35], v[36:37] offset0:176 offset1:248
	s_waitcnt vmcnt(23)
	ds_write_b128 v131, v[66:69] offset:4608
	s_waitcnt vmcnt(22)
	ds_write_b128 v131, v[70:73] offset:9216
	s_waitcnt vmcnt(21)
	ds_write_b128 v131, v[74:77] offset:5760
	s_waitcnt vmcnt(20)
	ds_write_b128 v131, v[78:81] offset:10368
	s_waitcnt vmcnt(19)
	ds_write_b128 v131, v[82:85] offset:6912
	s_waitcnt vmcnt(18)
	ds_write_b128 v131, v[86:89] offset:11520
	s_waitcnt vmcnt(17)
	ds_write_b128 v131, v[90:93] offset:8064
	s_waitcnt vmcnt(16)
	ds_write_b128 v131, v[94:97] offset:12672
	v_lshl_add_u64 v[58:59], v[114:115], 0, s[22:23]
	s_brev_b32 s19, 32
	v_add_co_u32_e32 v34, vcc, s19, v58
	s_mov_b32 s19, 0x4004000
	s_nop 0
	v_addc_co_u32_e32 v35, vcc, 0, v59, vcc
	v_add_co_u32_e32 v36, vcc, s19, v58
	s_mov_b32 s19, 0x4008000
	s_nop 0
	v_addc_co_u32_e32 v37, vcc, 0, v59, vcc
	v_add_co_u32_e32 v42, vcc, s19, v58
	s_mov_b32 s19, 0x400c000
	s_nop 0
	v_addc_co_u32_e32 v43, vcc, 0, v59, vcc
	v_add_co_u32_e32 v44, vcc, s19, v58
	s_mov_b32 s19, 0x4010000
	s_nop 0
	v_addc_co_u32_e32 v45, vcc, 0, v59, vcc
	v_add_co_u32_e32 v50, vcc, s19, v58
	s_mov_b32 s19, 0x4014000
	s_nop 0
	v_addc_co_u32_e32 v51, vcc, 0, v59, vcc
	v_add_co_u32_e32 v52, vcc, s19, v58
	s_mov_b32 s19, 0x4018000
	s_nop 0
	v_addc_co_u32_e32 v53, vcc, 0, v59, vcc
	v_add_co_u32_e32 v60, vcc, s19, v58
	s_mov_b32 s19, 0x401c000
	s_nop 0
	v_addc_co_u32_e32 v61, vcc, 0, v59, vcc
	v_add_co_u32_e32 v58, vcc, s19, v58
	v_lshl_add_u64 v[90:91], v[118:119], 0, s[4:5]
	s_nop 0
	v_addc_co_u32_e32 v59, vcc, 0, v59, vcc
	v_add_co_u32_e32 v66, vcc, s34, v90
	v_lshl_add_u64 v[94:95], v[120:121], 0, s[4:5]
	s_nop 0
	v_addc_co_u32_e32 v67, vcc, 0, v91, vcc
	v_add_co_u32_e32 v70, vcc, s34, v94
	global_load_dwordx4 v[38:41], v[34:35], off offset:512
	s_nop 0
	global_load_dwordx4 v[34:37], v[36:37], off offset:512
	v_addc_co_u32_e32 v71, vcc, 0, v95, vcc
	v_add_co_u32_e32 v74, vcc, s33, v90
	global_load_dwordx4 v[46:49], v[42:43], off offset:512
	s_nop 0
	global_load_dwordx4 v[42:45], v[44:45], off offset:512
	v_addc_co_u32_e32 v75, vcc, 0, v91, vcc
	v_add_co_u32_e32 v78, vcc, s33, v94
	global_load_dwordx4 v[54:57], v[50:51], off offset:512
	s_nop 0
	global_load_dwordx4 v[50:53], v[52:53], off offset:512
	v_addc_co_u32_e32 v79, vcc, 0, v95, vcc
	v_add_co_u32_e32 v82, vcc, s35, v90
	global_load_dwordx4 v[62:65], v[60:61], off offset:512
	s_nop 0
	global_load_dwordx4 v[58:61], v[58:59], off offset:512
	v_addc_co_u32_e32 v83, vcc, 0, v91, vcc
	v_add_co_u32_e32 v86, vcc, s35, v94
	global_load_dwordx4 v[66:69], v[66:67], off offset:256
	s_nop 0
	v_addc_co_u32_e32 v87, vcc, 0, v95, vcc
	v_add_co_u32_e32 v90, vcc, s86, v90
	global_load_dwordx4 v[70:73], v[70:71], off offset:256
	s_nop 0
	v_addc_co_u32_e32 v91, vcc, 0, v91, vcc
	v_add_co_u32_e32 v94, vcc, s86, v94
	global_load_dwordx4 v[74:77], v[74:75], off offset:256
	s_nop 0
	v_addc_co_u32_e32 v95, vcc, 0, v95, vcc
	global_load_dwordx4 v[78:81], v[78:79], off offset:256
	s_nop 0
	global_load_dwordx4 v[82:85], v[82:83], off offset:256
	s_nop 0
	global_load_dwordx4 v[86:89], v[86:87], off offset:256
	s_nop 0
	global_load_dwordx4 v[90:93], v[90:91], off offset:256
	s_nop 0
	global_load_dwordx4 v[94:97], v[94:95], off offset:256
	ds_read_b128 v[136:139], v132
	ds_read_b128 v[140:143], v132 offset:4608
	s_waitcnt lgkmcnt(0)
; #define LAS __attribute__((address_space(3)))
; __device__ __forceinline__ unsigned cvtpk(float lo, float hi) { f32x2 v = {lo, hi}; bf16x2_t b = __builtin_convertvector(v, bf16x2_t); return __builtin_bit_cast(unsigned, b); }
; #define MFMA32(a, b, c) __builtin_amdgcn_mfma_f32_32x32x16_bf16((a), (b), (c), 0, 0, 0)
;     ...
;                 if constexpr (AF32) {
; #pragma unroll
;                     for (int i = 0; i < 8; ++i) { const f32x4 x = xa[i]; q8[i] += (x[0] * x[0] + x[1] * x[1]) + (x[2] * x[2] + x[3] * x[3]);
;                         u32x2 w; w.x = cvtpk(x[0], x[1]); w.y = cvtpk(x[2], x[3]); *(LAS u32x2*)(SA + (4 * i + (lane >> 4)) * PITCH + 8 * (lane & 15)) = w; }
;                 } else {
; #pragma unroll
;                     for (int i = 0; i < 4; ++i) *(LAS u32x4*)(SA + (8 * i + (lane >> 3)) * PITCH + 16 * (lane & 7)) = ab[i];
;                 }
; #pragma unroll
;                 for (int i = 0; i < 4; ++i) { *(LAS u32x4*)(SB0 + (8 * i + (lane >> 3)) * PITCH + 16 * (lane & 7)) = bb0[i]; *(LAS u32x4*)(SB1 + (8 * i + (lane >> 3)) * PITCH + 16 * (lane & 7)) = bb1[i]; }
;                 __builtin_amdgcn_sched_barrier(0);
;                 if (kb + 1 < nb) SG_LOAD(kb + 1);
;                 __builtin_amdgcn_sched_barrier(0);
; #pragma unroll
;                 for (int j = 0; j < 4; ++j) {
;                     const bf16x8 af = *(const LAS bf16x8*)(SA + r32 * PITCH + 32 * j + 16 * hi);
;                     const bf16x8 f0 = *(const LAS bf16x8*)(SB0 + r32 * PITCH + 32 * j + 16 * hi), f1 = *(const LAS bf16x8*)(SB1 + r32 * PITCH + 32 * j + 16 * hi);
;                     acc0 = MFMA32(af, f0, acc0); acc1 = MFMA32(af, f1, acc1);
;                 }
	v_mfma_f32_32x32x16_bf16 v[2:17], v[136:139], v[140:143], v[2:17]
	ds_read_b128 v[140:143], v132 offset:9216
	s_waitcnt lgkmcnt(0)
	v_mfma_f32_32x32x16_bf16 v[18:33], v[136:139], v[140:143], v[18:33]
	ds_read_b128 v[136:139], v132 offset:32
	ds_read_b128 v[140:143], v132 offset:4640
	s_waitcnt lgkmcnt(0)
	v_mfma_f32_32x32x16_bf16 v[2:17], v[136:139], v[140:143], v[2:17]
	ds_read_b128 v[140:143], v132 offset:9248
	s_waitcnt lgkmcnt(0)
	v_mfma_f32_32x32x16_bf16 v[18:33], v[136:139], v[140:143], v[18:33]
	ds_read_b128 v[136:139], v132 offset:64
	ds_read_b128 v[140:143], v132 offset:4672
	s_waitcnt lgkmcnt(0)
	v_mfma_f32_32x32x16_bf16 v[2:17], v[136:139], v[140:143], v[2:17]
	ds_read_b128 v[140:143], v132 offset:9280
	s_waitcnt lgkmcnt(0)
	v_mfma_f32_32x32x16_bf16 v[18:33], v[136:139], v[140:143], v[18:33]
	ds_read_b128 v[136:139], v132 offset:96
	ds_read_b128 v[140:143], v132 offset:4704
	s_waitcnt lgkmcnt(0)
	v_mfma_f32_32x32x16_bf16 v[2:17], v[136:139], v[140:143], v[2:17]
	ds_read_b128 v[140:143], v132 offset:9312
	s_waitcnt lgkmcnt(0)
	v_mfma_f32_32x32x16_bf16 v[18:33], v[136:139], v[140:143], v[18:33]
	s_waitcnt vmcnt(31)
	v_cvt_pk_bf16_f32 v134, v148, v149
	v_mov_b32_e32 v136, v148
	v_mov_b32_e32 v148, v149
	s_waitcnt vmcnt(30)
	v_mov_b32_e32 v149, v145
	v_mov_b32_e32 v137, v144
	v_pk_mul_f32 v[148:149], v[148:149], v[148:149]
	v_cvt_pk_bf16_f32 v135, v150, v151
	v_pk_fma_f32 v[148:149], v[136:137], v[136:137], v[148:149]
	v_mov_b32_e32 v136, v150
	v_mov_b32_e32 v150, v151
	v_mov_b32_e32 v151, v147
	v_mov_b32_e32 v137, v146
	v_pk_mul_f32 v[150:151], v[150:151], v[150:151]
	v_cvt_pk_bf16_f32 v144, v144, v145
	v_pk_fma_f32 v[150:151], v[136:137], v[136:137], v[150:151]
	v_cvt_pk_bf16_f32 v145, v146, v147
	v_pk_add_f32 v[148:149], v[148:149], v[150:151]
	s_waitcnt vmcnt(29)
	v_mov_b32_e32 v146, v156
	v_pk_add_f32 v[108:109], v[108:109], v[148:149]
	v_mov_b32_e32 v148, v157
	s_waitcnt vmcnt(28)
	v_mov_b32_e32 v149, v153
	v_mov_b32_e32 v147, v152
	v_pk_mul_f32 v[148:149], v[148:149], v[148:149]
	v_mov_b32_e32 v150, v159
	v_mov_b32_e32 v151, v155
	v_pk_fma_f32 v[146:147], v[146:147], v[146:147], v[148:149]
	v_mov_b32_e32 v148, v158
	v_mov_b32_e32 v149, v154
	v_pk_mul_f32 v[150:151], v[150:151], v[150:151]
	ds_write2_b64 v130, v[134:135], v[144:145] offset1:72
	v_pk_fma_f32 v[148:149], v[148:149], v[148:149], v[150:151]
	v_cvt_pk_bf16_f32 v144, v156, v157
	v_pk_add_f32 v[146:147], v[146:147], v[148:149]
	v_cvt_pk_bf16_f32 v145, v158, v159
	v_pk_add_f32 v[110:111], v[110:111], v[146:147]
	v_cvt_pk_bf16_f32 v146, v152, v153
	v_cvt_pk_bf16_f32 v147, v154, v155
	s_waitcnt vmcnt(27)
	v_mov_b32_e32 v148, v179
	s_waitcnt vmcnt(26)
	v_mov_b32_e32 v149, v175
	ds_write2_b64 v130, v[144:145], v[146:147] offset0:144 offset1:216
	v_mov_b32_e32 v146, v178
	v_mov_b32_e32 v147, v174
	v_pk_mul_f32 v[148:149], v[148:149], v[148:149]
	v_mov_b32_e32 v150, v181
	v_mov_b32_e32 v151, v177
	v_pk_fma_f32 v[146:147], v[146:147], v[146:147], v[148:149]
	v_mov_b32_e32 v148, v180
	v_mov_b32_e32 v149, v176
	v_pk_mul_f32 v[150:151], v[150:151], v[150:151]
	v_cvt_pk_bf16_f32 v144, v178, v179
	v_pk_fma_f32 v[148:149], v[148:149], v[148:149], v[150:151]
	v_cvt_pk_bf16_f32 v145, v180, v181
	v_pk_add_f32 v[146:147], v[146:147], v[148:149]
	v_add_u32_e32 v134, 0x800, v130
	v_pk_add_f32 v[112:113], v[112:113], v[146:147]
	v_cvt_pk_bf16_f32 v146, v174, v175
	v_cvt_pk_bf16_f32 v147, v176, v177
	s_waitcnt vmcnt(25)
	v_mov_b32_e32 v148, v187
	s_waitcnt vmcnt(24)
	v_mov_b32_e32 v149, v183
	ds_write2_b64 v134, v[144:145], v[146:147] offset0:32 offset1:104
	v_mov_b32_e32 v146, v186
	v_mov_b32_e32 v147, v182
	v_pk_mul_f32 v[148:149], v[148:149], v[148:149]
	v_mov_b32_e32 v150, v189
	v_mov_b32_e32 v151, v185
	v_pk_fma_f32 v[146:147], v[146:147], v[146:147], v[148:149]
	v_mov_b32_e32 v148, v188
	v_mov_b32_e32 v149, v184
	v_pk_mul_f32 v[150:151], v[150:151], v[150:151]
	v_cvt_pk_bf16_f32 v144, v186, v187
	v_pk_fma_f32 v[148:149], v[148:149], v[148:149], v[150:151]
	v_cvt_pk_bf16_f32 v145, v188, v189
	v_pk_add_f32 v[146:147], v[146:147], v[148:149]
	s_nop 0
	v_pk_add_f32 v[116:117], v[116:117], v[146:147]
	v_cvt_pk_bf16_f32 v146, v182, v183
	v_cvt_pk_bf16_f32 v147, v184, v185
	ds_write2_b64 v134, v[144:145], v[146:147] offset0:176 offset1:248
	s_waitcnt vmcnt(23)
	ds_write_b128 v131, v[190:193] offset:4608
	s_waitcnt vmcnt(22)
	ds_write_b128 v131, v[194:197] offset:9216
	s_waitcnt vmcnt(21)
	ds_write_b128 v131, v[208:211] offset:5760
	s_waitcnt vmcnt(20)
	ds_write_b128 v131, v[212:215] offset:10368
	s_waitcnt vmcnt(19)
	ds_write_b128 v131, v[216:219] offset:6912
	s_waitcnt vmcnt(18)
	ds_write_b128 v131, v[220:223] offset:11520
	s_waitcnt vmcnt(17)
	ds_write_b128 v131, v[224:227] offset:8064
	s_waitcnt vmcnt(16)
; #define LAS __attribute__((address_space(3)))
; #define MFMA32(a, b, c) __builtin_amdgcn_mfma_f32_32x32x16_bf16((a), (b), (c), 0, 0, 0)
;     ...
;                 for (int i = 0; i < 4; ++i) { *(LAS u32x4*)(SB0 + (8 * i + (lane >> 3)) * PITCH + 16 * (lane & 7)) = bb0[i]; *(LAS u32x4*)(SB1 + (8 * i + (lane >> 3)) * PITCH + 16 * (lane & 7)) = bb1[i]; }
;                 __builtin_amdgcn_sched_barrier(0);
;                 if (kb + 1 < nb) SG_LOAD(kb + 1);
;                 __builtin_amdgcn_sched_barrier(0);
; #pragma unroll
;                 for (int j = 0; j < 4; ++j) {
;                     const bf16x8 af = *(const LAS bf16x8*)(SA + r32 * PITCH + 32 * j + 16 * hi);
;                     const bf16x8 f0 = *(const LAS bf16x8*)(SB0 + r32 * PITCH + 32 * j + 16 * hi), f1 = *(const LAS bf16x8*)(SB1 + r32 * PITCH + 32 * j + 16 * hi);
;                     acc0 = MFMA32(af, f0, acc0); acc1 = MFMA32(af, f1, acc1);
;                 }
	ds_write_b128 v131, v[228:231] offset:12672
	v_lshl_add_u64 v[182:183], v[114:115], 0, s[22:23]
	s_brev_b32 s19, 32
	v_add_co_u32_e32 v144, vcc, s19, v182
	s_mov_b32 s19, 0x4004000
	s_nop 0
	v_addc_co_u32_e32 v145, vcc, 0, v183, vcc
	v_add_co_u32_e32 v146, vcc, s19, v182
	s_mov_b32 s19, 0x4008000
	s_nop 0
	v_addc_co_u32_e32 v147, vcc, 0, v183, vcc
	v_add_co_u32_e32 v152, vcc, s19, v182
	s_mov_b32 s19, 0x400c000
	s_nop 0
	v_addc_co_u32_e32 v153, vcc, 0, v183, vcc
	v_add_co_u32_e32 v154, vcc, s19, v182
	s_mov_b32 s19, 0x4010000
	s_nop 0
	v_addc_co_u32_e32 v155, vcc, 0, v183, vcc
	v_add_co_u32_e32 v174, vcc, s19, v182
	s_mov_b32 s19, 0x4014000
	s_nop 0
	v_addc_co_u32_e32 v175, vcc, 0, v183, vcc
	v_add_co_u32_e32 v176, vcc, s19, v182
	s_mov_b32 s19, 0x4018000
	s_nop 0
	v_addc_co_u32_e32 v177, vcc, 0, v183, vcc
	v_add_co_u32_e32 v184, vcc, s19, v182
	s_mov_b32 s19, 0x401c000
	s_nop 0
	v_addc_co_u32_e32 v185, vcc, 0, v183, vcc
	v_add_co_u32_e32 v182, vcc, s19, v182
	v_lshl_add_u64 v[224:225], v[118:119], 0, s[4:5]
	s_nop 0
	v_addc_co_u32_e32 v183, vcc, 0, v183, vcc
	v_add_co_u32_e32 v190, vcc, s34, v224
	v_lshl_add_u64 v[228:229], v[120:121], 0, s[4:5]
	s_nop 0
	v_addc_co_u32_e32 v191, vcc, 0, v225, vcc
	v_add_co_u32_e32 v194, vcc, s34, v228
	global_load_dwordx4 v[148:151], v[144:145], off offset:768
	s_nop 0
	global_load_dwordx4 v[144:147], v[146:147], off offset:768
	v_addc_co_u32_e32 v195, vcc, 0, v229, vcc
	v_add_co_u32_e32 v208, vcc, s33, v224
	global_load_dwordx4 v[156:159], v[152:153], off offset:768
	s_nop 0
	global_load_dwordx4 v[152:155], v[154:155], off offset:768
	v_addc_co_u32_e32 v209, vcc, 0, v225, vcc
	v_add_co_u32_e32 v212, vcc, s33, v228
	global_load_dwordx4 v[178:181], v[174:175], off offset:768
	s_nop 0
	global_load_dwordx4 v[174:177], v[176:177], off offset:768
	v_addc_co_u32_e32 v213, vcc, 0, v229, vcc
	v_add_co_u32_e32 v216, vcc, s35, v224
	global_load_dwordx4 v[186:189], v[184:185], off offset:768
	s_nop 0
	global_load_dwordx4 v[182:185], v[182:183], off offset:768
	v_addc_co_u32_e32 v217, vcc, 0, v225, vcc
	v_add_co_u32_e32 v220, vcc, s35, v228
	global_load_dwordx4 v[190:193], v[190:191], off offset:384
	s_nop 0
	v_addc_co_u32_e32 v221, vcc, 0, v229, vcc
	v_add_co_u32_e32 v224, vcc, s86, v224
	global_load_dwordx4 v[194:197], v[194:195], off offset:384
	s_nop 0
	v_addc_co_u32_e32 v225, vcc, 0, v225, vcc
	v_add_co_u32_e32 v228, vcc, s86, v228
	global_load_dwordx4 v[208:211], v[208:209], off offset:384
	s_nop 0
	v_addc_co_u32_e32 v229, vcc, 0, v229, vcc
	global_load_dwordx4 v[212:215], v[212:213], off offset:384
	s_nop 0
	global_load_dwordx4 v[216:219], v[216:217], off offset:384
	s_nop 0
	global_load_dwordx4 v[220:223], v[220:221], off offset:384
	s_nop 0
	global_load_dwordx4 v[224:227], v[224:225], off offset:384
	s_nop 0
	global_load_dwordx4 v[228:231], v[228:229], off offset:384
	ds_read_b128 v[136:139], v132
	ds_read_b128 v[140:143], v132 offset:4608
	s_add_u32 s22, s22, 0x200
	s_addc_u32 s23, s23, 0
	v_lshl_add_u64 v[118:119], v[118:119], 0, s[0:1]
	v_lshl_add_u64 v[120:121], v[120:121], 0, s[0:1]
	v_lshl_add_u64 v[118:119], v[118:119], 0, s[0:1]
	v_lshl_add_u64 v[120:121], v[120:121], 0, s[0:1]
	s_cmpk_eq_i32 s22, 0x600
	s_waitcnt lgkmcnt(0)
	v_mfma_f32_32x32x16_bf16 v[2:17], v[136:139], v[140:143], v[2:17]
	ds_read_b128 v[140:143], v132 offset:9216
	s_waitcnt lgkmcnt(0)
	v_mfma_f32_32x32x16_bf16 v[18:33], v[136:139], v[140:143], v[18:33]
	ds_read_b128 v[136:139], v132 offset:32
	ds_read_b128 v[140:143], v132 offset:4640
	s_waitcnt lgkmcnt(0)
	v_mfma_f32_32x32x16_bf16 v[2:17], v[136:139], v[140:143], v[2:17]
	ds_read_b128 v[140:143], v132 offset:9248
	s_waitcnt lgkmcnt(0)
	v_mfma_f32_32x32x16_bf16 v[18:33], v[136:139], v[140:143], v[18:33]
	ds_read_b128 v[136:139], v132 offset:64
	ds_read_b128 v[140:143], v132 offset:4672
	s_waitcnt lgkmcnt(0)
	v_mfma_f32_32x32x16_bf16 v[2:17], v[136:139], v[140:143], v[2:17]
	ds_read_b128 v[140:143], v132 offset:9280
	s_waitcnt lgkmcnt(0)
	v_mfma_f32_32x32x16_bf16 v[18:33], v[136:139], v[140:143], v[18:33]
	ds_read_b128 v[136:139], v132 offset:96
	ds_read_b128 v[140:143], v132 offset:4704
	s_waitcnt lgkmcnt(0)
	v_mfma_f32_32x32x16_bf16 v[2:17], v[136:139], v[140:143], v[2:17]
	ds_read_b128 v[140:143], v132 offset:9312
	s_waitcnt lgkmcnt(0)
	v_mfma_f32_32x32x16_bf16 v[18:33], v[136:139], v[140:143], v[18:33]
	s_cbranch_scc0 .LBB0_1246
; #define LAS __attribute__((address_space(3)))
; __device__ __forceinline__ unsigned cvtpk(float lo, float hi) { f32x2 v = {lo, hi}; bf16x2_t b = __builtin_convertvector(v, bf16x2_t); return __builtin_bit_cast(unsigned, b); }
; #define MFMA32(a, b, c) __builtin_amdgcn_mfma_f32_32x32x16_bf16((a), (b), (c), 0, 0, 0)
;     ...
;                 if constexpr (AF32) {
; #pragma unroll
;                     for (int i = 0; i < 8; ++i) { const f32x4 x = xa[i]; q8[i] += (x[0] * x[0] + x[1] * x[1]) + (x[2] * x[2] + x[3] * x[3]);
;                         u32x2 w; w.x = cvtpk(x[0], x[1]); w.y = cvtpk(x[2], x[3]); *(LAS u32x2*)(SA + (4 * i + (lane >> 4)) * PITCH + 8 * (lane & 15)) = w; }
;                 } else {
; #pragma unroll
;                     for (int i = 0; i < 4; ++i) *(LAS u32x4*)(SA + (8 * i + (lane >> 3)) * PITCH + 16 * (lane & 7)) = ab[i];
;                 }
; #pragma unroll
;                 for (int i = 0; i < 4; ++i) { *(LAS u32x4*)(SB0 + (8 * i + (lane >> 3)) * PITCH + 16 * (lane & 7)) = bb0[i]; *(LAS u32x4*)(SB1 + (8 * i + (lane >> 3)) * PITCH + 16 * (lane & 7)) = bb1[i]; }
;                 __builtin_amdgcn_sched_barrier(0);
;                 if (kb + 1 < nb) SG_LOAD(kb + 1);
;                 __builtin_amdgcn_sched_barrier(0);
; #pragma unroll
;                 for (int j = 0; j < 4; ++j) {
;                     const bf16x8 af = *(const LAS bf16x8*)(SA + r32 * PITCH + 32 * j + 16 * hi);
;                     const bf16x8 f0 = *(const LAS bf16x8*)(SB0 + r32 * PITCH + 32 * j + 16 * hi), f1 = *(const LAS bf16x8*)(SB1 + r32 * PITCH + 32 * j + 16 * hi);
;                     acc0 = MFMA32(af, f0, acc0); acc1 = MFMA32(af, f1, acc1);
;                 }
	s_waitcnt vmcnt(31)
	v_cvt_pk_bf16_f32 v134, v38, v39
	v_mov_b32_e32 v136, v38
	v_mov_b32_e32 v38, v39
	s_waitcnt vmcnt(30)
	v_mov_b32_e32 v39, v35
	v_mov_b32_e32 v137, v34
	v_pk_mul_f32 v[38:39], v[38:39], v[38:39]
	v_cvt_pk_bf16_f32 v135, v40, v41
	v_pk_fma_f32 v[38:39], v[136:137], v[136:137], v[38:39]
	v_mov_b32_e32 v136, v40
	v_mov_b32_e32 v40, v41
	v_mov_b32_e32 v41, v37
	v_mov_b32_e32 v137, v36
	v_pk_mul_f32 v[40:41], v[40:41], v[40:41]
	v_cvt_pk_bf16_f32 v34, v34, v35
	v_pk_fma_f32 v[40:41], v[136:137], v[136:137], v[40:41]
	v_cvt_pk_bf16_f32 v35, v36, v37
	v_pk_add_f32 v[38:39], v[38:39], v[40:41]
	s_waitcnt vmcnt(29)
	v_mov_b32_e32 v36, v46
	v_pk_add_f32 v[108:109], v[108:109], v[38:39]
	v_mov_b32_e32 v38, v47
	s_waitcnt vmcnt(28)
	v_mov_b32_e32 v39, v43
	v_mov_b32_e32 v37, v42
	v_pk_mul_f32 v[38:39], v[38:39], v[38:39]
	v_mov_b32_e32 v40, v49
	v_mov_b32_e32 v41, v45
	v_pk_fma_f32 v[36:37], v[36:37], v[36:37], v[38:39]
	v_mov_b32_e32 v38, v48
	v_mov_b32_e32 v39, v44
	v_pk_mul_f32 v[40:41], v[40:41], v[40:41]
	ds_write2_b64 v130, v[134:135], v[34:35] offset1:72
	v_pk_fma_f32 v[38:39], v[38:39], v[38:39], v[40:41]
	v_cvt_pk_bf16_f32 v34, v46, v47
	v_pk_add_f32 v[36:37], v[36:37], v[38:39]
	v_cvt_pk_bf16_f32 v35, v48, v49
	v_pk_add_f32 v[110:111], v[110:111], v[36:37]
	v_cvt_pk_bf16_f32 v36, v42, v43
	v_cvt_pk_bf16_f32 v37, v44, v45
	s_waitcnt vmcnt(27)
	v_mov_b32_e32 v38, v55
	s_waitcnt vmcnt(26)
	v_mov_b32_e32 v39, v51
	ds_write2_b64 v130, v[34:35], v[36:37] offset0:144 offset1:216
	v_mov_b32_e32 v36, v54
	v_mov_b32_e32 v37, v50
	v_pk_mul_f32 v[38:39], v[38:39], v[38:39]
	v_mov_b32_e32 v40, v57
	v_mov_b32_e32 v41, v53
	v_pk_fma_f32 v[36:37], v[36:37], v[36:37], v[38:39]
	v_mov_b32_e32 v38, v56
	v_mov_b32_e32 v39, v52
	v_pk_mul_f32 v[40:41], v[40:41], v[40:41]
	v_cvt_pk_bf16_f32 v34, v54, v55
	v_pk_fma_f32 v[38:39], v[38:39], v[38:39], v[40:41]
	v_cvt_pk_bf16_f32 v35, v56, v57
	v_pk_add_f32 v[36:37], v[36:37], v[38:39]
	v_add_u32_e32 v134, 0x800, v130
	v_pk_add_f32 v[112:113], v[112:113], v[36:37]
	v_cvt_pk_bf16_f32 v36, v50, v51
	v_cvt_pk_bf16_f32 v37, v52, v53
	s_waitcnt vmcnt(25)
	v_mov_b32_e32 v38, v63
	s_waitcnt vmcnt(24)
	v_mov_b32_e32 v39, v59
	ds_write2_b64 v134, v[34:35], v[36:37] offset0:32 offset1:104
	v_mov_b32_e32 v36, v62
	v_mov_b32_e32 v37, v58
	v_pk_mul_f32 v[38:39], v[38:39], v[38:39]
	v_mov_b32_e32 v40, v65
	v_mov_b32_e32 v41, v61
	v_pk_fma_f32 v[36:37], v[36:37], v[36:37], v[38:39]
	v_mov_b32_e32 v38, v64
	v_mov_b32_e32 v39, v60
	v_pk_mul_f32 v[40:41], v[40:41], v[40:41]
	v_cvt_pk_bf16_f32 v34, v62, v63
	v_pk_fma_f32 v[38:39], v[38:39], v[38:39], v[40:41]
	v_cvt_pk_bf16_f32 v35, v64, v65
	v_pk_add_f32 v[36:37], v[36:37], v[38:39]
	s_nop 0
	v_pk_add_f32 v[116:117], v[116:117], v[36:37]
	v_cvt_pk_bf16_f32 v36, v58, v59
	v_cvt_pk_bf16_f32 v37, v60, v61
	ds_write2_b64 v134, v[34:35], v[36:37] offset0:176 offset1:248
	s_waitcnt vmcnt(23)
	ds_write_b128 v131, v[66:69] offset:4608
	s_waitcnt vmcnt(22)
	ds_write_b128 v131, v[70:73] offset:9216
	s_waitcnt vmcnt(21)
	ds_write_b128 v131, v[74:77] offset:5760
	s_waitcnt vmcnt(20)
	ds_write_b128 v131, v[78:81] offset:10368
	s_waitcnt vmcnt(19)
	ds_write_b128 v131, v[82:85] offset:6912
	s_waitcnt vmcnt(18)
	ds_write_b128 v131, v[86:89] offset:11520
	s_waitcnt vmcnt(17)
	ds_write_b128 v131, v[90:93] offset:8064
	s_waitcnt vmcnt(16)
	ds_write_b128 v131, v[94:97] offset:12672
	ds_read_b128 v[136:139], v132
	ds_read_b128 v[140:143], v132 offset:4608
	s_waitcnt lgkmcnt(0)
	v_mfma_f32_32x32x16_bf16 v[2:17], v[136:139], v[140:143], v[2:17]
	ds_read_b128 v[140:143], v132 offset:9216
	s_waitcnt lgkmcnt(0)
	v_mfma_f32_32x32x16_bf16 v[18:33], v[136:139], v[140:143], v[18:33]
	ds_read_b128 v[136:139], v132 offset:32
	ds_read_b128 v[140:143], v132 offset:4640
	s_waitcnt lgkmcnt(0)
	v_mfma_f32_32x32x16_bf16 v[2:17], v[136:139], v[140:143], v[2:17]
	ds_read_b128 v[140:143], v132 offset:9248
	s_waitcnt lgkmcnt(0)
	v_mfma_f32_32x32x16_bf16 v[18:33], v[136:139], v[140:143], v[18:33]
	ds_read_b128 v[136:139], v132 offset:64
	ds_read_b128 v[140:143], v132 offset:4672
	s_waitcnt lgkmcnt(0)
	v_mfma_f32_32x32x16_bf16 v[2:17], v[136:139], v[140:143], v[2:17]
	ds_read_b128 v[140:143], v132 offset:9280
	s_waitcnt lgkmcnt(0)
	v_mfma_f32_32x32x16_bf16 v[18:33], v[136:139], v[140:143], v[18:33]
	ds_read_b128 v[136:139], v132 offset:96
	ds_read_b128 v[140:143], v132 offset:4704
	s_waitcnt lgkmcnt(0)
	v_mfma_f32_32x32x16_bf16 v[2:17], v[136:139], v[140:143], v[2:17]
	ds_read_b128 v[140:143], v132 offset:9312
	s_waitcnt lgkmcnt(0)
	v_mfma_f32_32x32x16_bf16 v[18:33], v[136:139], v[140:143], v[18:33]
	s_waitcnt vmcnt(15)
	v_cvt_pk_bf16_f32 v114, v148, v149
	v_cvt_pk_bf16_f32 v115, v150, v151
	s_waitcnt vmcnt(14)
	v_cvt_pk_bf16_f32 v118, v144, v145
	v_cvt_pk_bf16_f32 v119, v146, v147
	ds_write2_b64 v130, v[114:115], v[118:119] offset1:72
	s_waitcnt vmcnt(13)
	v_cvt_pk_bf16_f32 v114, v156, v157
	v_cvt_pk_bf16_f32 v115, v158, v159
	s_waitcnt vmcnt(12)
	v_cvt_pk_bf16_f32 v118, v152, v153
	v_cvt_pk_bf16_f32 v119, v154, v155
	ds_write2_b64 v130, v[114:115], v[118:119] offset0:144 offset1:216
	s_waitcnt vmcnt(11)
	v_cvt_pk_bf16_f32 v114, v178, v179
	v_cvt_pk_bf16_f32 v115, v180, v181
	s_waitcnt vmcnt(10)
	v_cvt_pk_bf16_f32 v118, v174, v175
	v_cvt_pk_bf16_f32 v119, v176, v177
	ds_write2_b64 v134, v[114:115], v[118:119] offset0:32 offset1:104
	s_waitcnt vmcnt(9)
	v_cvt_pk_bf16_f32 v114, v186, v187
	v_cvt_pk_bf16_f32 v115, v188, v189
	s_waitcnt vmcnt(8)
; #define LAS __attribute__((address_space(3)))
; __device__ __forceinline__ unsigned cvtpk(float lo, float hi) { f32x2 v = {lo, hi}; bf16x2_t b = __builtin_convertvector(v, bf16x2_t); return __builtin_bit_cast(unsigned, b); }
; #define MFMA32(a, b, c) __builtin_amdgcn_mfma_f32_32x32x16_bf16((a), (b), (c), 0, 0, 0)
;     ...
;                     for (int i = 0; i < 8; ++i) { const f32x4 x = xa[i]; q8[i] += (x[0] * x[0] + x[1] * x[1]) + (x[2] * x[2] + x[3] * x[3]);
;                         u32x2 w; w.x = cvtpk(x[0], x[1]); w.y = cvtpk(x[2], x[3]); *(LAS u32x2*)(SA + (4 * i + (lane >> 4)) * PITCH + 8 * (lane & 15)) = w; }
;                 } else {
; #pragma unroll
;                     for (int i = 0; i < 4; ++i) *(LAS u32x4*)(SA + (8 * i + (lane >> 3)) * PITCH + 16 * (lane & 7)) = ab[i];
;                 }
; #pragma unroll
;                 for (int i = 0; i < 4; ++i) { *(LAS u32x4*)(SB0 + (8 * i + (lane >> 3)) * PITCH + 16 * (lane & 7)) = bb0[i]; *(LAS u32x4*)(SB1 + (8 * i + (lane >> 3)) * PITCH + 16 * (lane & 7)) = bb1[i]; }
;                 __builtin_amdgcn_sched_barrier(0);
;                 if (kb + 1 < nb) SG_LOAD(kb + 1);
;                 __builtin_amdgcn_sched_barrier(0);
; #pragma unroll
;                 for (int j = 0; j < 4; ++j) {
;                     const bf16x8 af = *(const LAS bf16x8*)(SA + r32 * PITCH + 32 * j + 16 * hi);
;                     const bf16x8 f0 = *(const LAS bf16x8*)(SB0 + r32 * PITCH + 32 * j + 16 * hi), f1 = *(const LAS bf16x8*)(SB1 + r32 * PITCH + 32 * j + 16 * hi);
;                     acc0 = MFMA32(af, f0, acc0); acc1 = MFMA32(af, f1, acc1);
;                 }
	v_cvt_pk_bf16_f32 v118, v182, v183
	v_cvt_pk_bf16_f32 v119, v184, v185
	ds_write2_b64 v134, v[114:115], v[118:119] offset0:176 offset1:248
	s_waitcnt vmcnt(7)
	ds_write_b128 v131, v[190:193] offset:4608
	s_waitcnt vmcnt(6)
	ds_write_b128 v131, v[194:197] offset:9216
	s_waitcnt vmcnt(5)
	ds_write_b128 v131, v[208:211] offset:5760
	s_waitcnt vmcnt(4)
	ds_write_b128 v131, v[212:215] offset:10368
	s_waitcnt vmcnt(3)
	ds_write_b128 v131, v[216:219] offset:6912
	s_waitcnt vmcnt(2)
	ds_write_b128 v131, v[220:223] offset:11520
	s_waitcnt vmcnt(1)
	ds_write_b128 v131, v[224:227] offset:8064
	s_waitcnt vmcnt(0)
	ds_write_b128 v131, v[228:231] offset:12672
	v_mov_b32_e32 v191, v182
	v_mov_b32_e32 v182, v187
	v_mov_b32_e32 v187, v184
	v_mov_b32_e32 v184, v189
	v_mov_b32_e32 v190, v186
	v_pk_mul_f32 v[182:183], v[182:183], v[182:183]
	v_mov_b32_e32 v186, v188
	v_pk_mul_f32 v[184:185], v[184:185], v[184:185]
	v_pk_fma_f32 v[182:183], v[190:191], v[190:191], v[182:183]
	v_pk_fma_f32 v[184:185], v[186:187], v[186:187], v[184:185]
	s_nop 0
	v_pk_add_f32 v[182:183], v[182:183], v[184:185]
	v_mov_b32_e32 v185, v174
	v_mov_b32_e32 v174, v179
	v_mov_b32_e32 v179, v176
	v_mov_b32_e32 v176, v181
	v_mov_b32_e32 v184, v178
	v_pk_mul_f32 v[174:175], v[174:175], v[174:175]
	v_mov_b32_e32 v178, v180
	v_pk_mul_f32 v[176:177], v[176:177], v[176:177]
	v_pk_fma_f32 v[174:175], v[184:185], v[184:185], v[174:175]
	v_pk_fma_f32 v[176:177], v[178:179], v[178:179], v[176:177]
	v_pk_add_f32 v[182:183], v[116:117], v[182:183]
	v_pk_add_f32 v[174:175], v[174:175], v[176:177]
	v_mov_b32_e32 v177, v152
	v_mov_b32_e32 v152, v157
	v_mov_b32_e32 v157, v154
	v_mov_b32_e32 v154, v159
	v_mov_b32_e32 v176, v156
	v_pk_mul_f32 v[152:153], v[152:153], v[152:153]
	v_mov_b32_e32 v156, v158
	v_pk_mul_f32 v[154:155], v[154:155], v[154:155]
	v_pk_fma_f32 v[152:153], v[176:177], v[176:177], v[152:153]
	v_pk_fma_f32 v[154:155], v[156:157], v[156:157], v[154:155]
	v_pk_add_f32 v[174:175], v[112:113], v[174:175]
	v_pk_add_f32 v[152:153], v[152:153], v[154:155]
	v_mov_b32_e32 v155, v144
	v_mov_b32_e32 v144, v149
	v_mov_b32_e32 v149, v146
	v_mov_b32_e32 v146, v151
	v_mov_b32_e32 v154, v148
	v_pk_mul_f32 v[144:145], v[144:145], v[144:145]
	v_mov_b32_e32 v148, v150
	v_pk_mul_f32 v[146:147], v[146:147], v[146:147]
	v_pk_fma_f32 v[144:145], v[154:155], v[154:155], v[144:145]
	v_pk_fma_f32 v[146:147], v[148:149], v[148:149], v[146:147]
	v_pk_add_f32 v[152:153], v[110:111], v[152:153]
	v_pk_add_f32 v[144:145], v[144:145], v[146:147]
	s_nop 0
	v_pk_add_f32 v[144:145], v[108:109], v[144:145]
	ds_read_b128 v[146:149], v132
	ds_read_b128 v[154:157], v132 offset:4608
	s_ashr_i32 s19, s18, 31
	s_waitcnt lgkmcnt(0)
	v_mfma_f32_32x32x16_bf16 v[2:17], v[146:149], v[154:157], v[2:17]
	ds_read_b128 v[154:157], v132 offset:9216
	s_waitcnt lgkmcnt(0)
	v_mfma_f32_32x32x16_bf16 v[18:33], v[146:149], v[154:157], v[18:33]
	ds_read_b128 v[146:149], v132 offset:32
	ds_read_b128 v[154:157], v132 offset:4640
	s_waitcnt lgkmcnt(0)
	v_mfma_f32_32x32x16_bf16 v[2:17], v[146:149], v[154:157], v[2:17]
	ds_read_b128 v[154:157], v132 offset:9248
	s_waitcnt lgkmcnt(0)
	v_mfma_f32_32x32x16_bf16 v[18:33], v[146:149], v[154:157], v[18:33]
	ds_read_b128 v[146:149], v132 offset:64
	ds_read_b128 v[154:157], v132 offset:4672
	s_waitcnt lgkmcnt(0)
	v_mfma_f32_32x32x16_bf16 v[2:17], v[146:149], v[154:157], v[2:17]
	ds_read_b128 v[154:157], v132 offset:9280
	s_waitcnt lgkmcnt(0)
	v_mfma_f32_32x32x16_bf16 v[18:33], v[146:149], v[154:157], v[18:33]
	ds_read_b128 v[146:149], v132 offset:96
	ds_read_b128 v[154:157], v132 offset:4704
	s_waitcnt lgkmcnt(0)
	v_mfma_f32_32x32x16_bf16 v[2:17], v[146:149], v[154:157], v[2:17]
	ds_read_b128 v[154:157], v132 offset:9312
	s_waitcnt lgkmcnt(0)
	v_mfma_f32_32x32x16_bf16 v[18:33], v[146:149], v[154:157], v[18:33]
	v_mov_b32_e32 v34, v144
	v_mov_b32_e32 v35, v145
	v_mov_b32_e32 v36, v146
	v_mov_b32_e32 v37, v147
	v_mov_b32_e32 v38, v148
	v_mov_b32_e32 v39, v149
	v_mov_b32_e32 v40, v150
	v_mov_b32_e32 v41, v151
	v_mov_b32_e32 v42, v152
	v_mov_b32_e32 v43, v153
	v_mov_b32_e32 v44, v154
	v_mov_b32_e32 v45, v155
	v_mov_b32_e32 v46, v156
	v_mov_b32_e32 v47, v157
	v_mov_b32_e32 v48, v158
	v_mov_b32_e32 v49, v159
	v_mov_b32_e32 v50, v174
	v_mov_b32_e32 v51, v175
	v_mov_b32_e32 v52, v176
	v_mov_b32_e32 v53, v177
	v_mov_b32_e32 v54, v178
	v_mov_b32_e32 v55, v179
	v_mov_b32_e32 v56, v180
	v_mov_b32_e32 v57, v181
	v_mov_b32_e32 v58, v182
	v_mov_b32_e32 v59, v183
	v_mov_b32_e32 v60, v184
	v_mov_b32_e32 v61, v185
	v_mov_b32_e32 v62, v186
	v_mov_b32_e32 v63, v187
	v_mov_b32_e32 v64, v188
	v_mov_b32_e32 v65, v189
	v_mov_b32_e32 v66, v190
	v_mov_b32_e32 v67, v191
	v_mov_b32_e32 v68, v192
	v_mov_b32_e32 v69, v193
	v_mov_b32_e32 v70, v194
	v_mov_b32_e32 v71, v195
	v_mov_b32_e32 v72, v196
	v_mov_b32_e32 v73, v197
	v_mov_b32_e32 v74, v208
	v_mov_b32_e32 v75, v209
	v_mov_b32_e32 v76, v210
	v_mov_b32_e32 v77, v211
	v_mov_b32_e32 v78, v212
	v_mov_b32_e32 v79, v213
	v_mov_b32_e32 v80, v214
	v_mov_b32_e32 v81, v215
	v_mov_b32_e32 v82, v216
	v_mov_b32_e32 v83, v217
	v_mov_b32_e32 v84, v218
	v_mov_b32_e32 v85, v219
	v_mov_b32_e32 v86, v220
	v_mov_b32_e32 v87, v221
	v_mov_b32_e32 v88, v222
	v_mov_b32_e32 v89, v223
	v_mov_b32_e32 v90, v224
	v_mov_b32_e32 v91, v225
	v_mov_b32_e32 v92, v226
	v_mov_b32_e32 v93, v227
	v_mov_b32_e32 v94, v228
	v_mov_b32_e32 v95, v229
	v_mov_b32_e32 v96, v230
	v_mov_b32_e32 v97, v231
	s_branch .LBB0_1249
